# mixer schedule variant: summary wait tied to first L part; even CLPP bins start with a pool part (PCLQ), odd CPQL
# speedup vs baseline: 1.0342x; 1.0006x over previous
.LBB0_512:
	v_writelane_b32 v255, 0, 43
	v_cmp_eq_u32_e64 s[4:5], 0, v146
	s_cmp_lt_i32 s39, 1
	s_nop 0
	v_writelane_b32 v254, s4, 50
	s_nop 1
	v_writelane_b32 v254, s5, 51
	v_writelane_b32 v254, s56, 52
	s_nop 1
	v_writelane_b32 v254, s57, 53
	s_cbranch_scc1 .LBB0_665
	v_readlane_b32 s4, v252, 7
	s_add_i32 s33, s33, s4
	s_add_u32 s4, s44, 0x300000
	s_addc_u32 s5, s45, 0
	v_writelane_b32 v254, s4, 54
	s_mov_b32 s25, s97
	s_mul_i32 s23, s56, 0x7c00
	v_writelane_b32 v254, s5, 55
	s_add_u32 s4, s44, 0x380000
	s_addc_u32 s5, s45, 0
	v_writelane_b32 v254, s4, 56
	s_mov_b32 s40, 0
	s_mov_b64 s[58:59], 0
	v_writelane_b32 v254, s5, 57
	s_add_u32 s4, s44, 0x1e00000
	s_addc_u32 s5, s45, 0
	s_cmp_gt_i32 s38, 31
	v_writelane_b32 v254, s4, 58
	s_cselect_b64 s[34:35], -1, 0
	s_cmp_gt_u32 s38, 63
	v_writelane_b32 v254, s5, 59
	s_cselect_b64 s[4:5], -1, 0
	v_writelane_b32 v254, s4, 60
	s_cmpk_gt_u32 s38, 0x9f
	s_nop 0
	v_writelane_b32 v254, s5, 61
	s_cselect_b64 s[4:5], -1, 0
	v_writelane_b32 v254, s4, 62
	s_lshl_b32 s96, s56, 6
	s_add_i32 s22, s38, 32
	v_writelane_b32 v254, s5, 63
	s_lshl_b32 s4, s38, 1
	s_add_i32 s5, s4, 0xffffff7e
	v_writelane_b32 v255, s5, 0
	v_writelane_b32 v255, s4, 1
	s_sub_i32 s4, s4, 33
	v_writelane_b32 v255, s4, 2
	s_lshl_b64 s[4:5], s[96:97], 2
	s_add_u32 s4, s44, s4
	s_addc_u32 s5, s45, s5
	s_add_u32 s28, s4, 0x8000
	s_addc_u32 s29, s5, 0
	s_lshl_b32 s24, s56, 8
	s_lshl_b64 s[4:5], s[24:25], 2
	s_add_u32 s36, s92, s4
	s_addc_u32 s37, s93, s5
	v_writelane_b32 v255, s36, 3
	s_nop 1
	v_writelane_b32 v255, s37, 4
	s_add_u32 s36, s94, s4
	s_addc_u32 s37, s95, s5
	v_writelane_b32 v255, s36, 5
	s_add_u32 s4, s26, s4
	s_addc_u32 s5, s27, s5
	v_writelane_b32 v255, s37, 6
	v_writelane_b32 v255, s4, 7
	s_nop 1
	v_writelane_b32 v255, s5, 8
	s_add_u32 s4, s44, 0x1e00600
	s_addc_u32 s5, s45, 0
	v_writelane_b32 v255, s4, 9
	s_nop 1
	v_writelane_b32 v255, s5, 10
	s_add_u32 s4, s44, 0x1e00400
	s_addc_u32 s5, s45, 0
	s_add_u32 s25, s44, 0x40000
	s_addc_u32 s41, s45, 0
	s_lshl_b32 s36, s56, 13
	v_writelane_b32 v255, s4, 11
	s_add_u32 s90, s90, s23
	s_addc_u32 s91, s91, 0
	v_writelane_b32 v255, s5, 12
	s_mov_b64 s[56:57], 0
	s_mov_b64 s[26:27], -1
	s_and_b64 vcc, exec, s[30:31]
	s_cbranch_vccz .LBB0_515

.LBB0_528:
	s_and_b64 vcc, exec, s[26:27]
	s_mov_b32 s4, s22
	s_cbranch_vccz .LBB0_530
	s_bitcmp1_b32 s38, 0
	s_movk_i32 s64, 0x2012
	s_cmovk_i32 s64, 0x221
	s_movk_i32 s23, 0x2001
	s_cmovk_i32 s23, 0x210
	s_lshl_b32 s4, s40, 2
	s_lshr_b32 s64, s64, s4
	s_and_b32 s64, s64, 15
	s_lshr_b32 s23, s23, s4
	s_and_b32 s23, s23, 15
	v_readlane_b32 s5, v255, 0
	s_nop 0
	s_add_i32 s5, s5, s23
	s_add_i32 s5, s5, 1
	s_cmp_eq_u32 s23, 0
	s_cselect_b32 s4, s22, s5

.LBB0_539:
	s_cmp_lg_u32 s64, 0
	s_cbranch_scc1 .LBB0_557
	v_readlane_b32 s4, v255, 43
	s_nop 1
	s_cmp_lg_u32 s4, 0
	s_cbranch_scc1 .LBB0_557
	s_nop 0
	v_writelane_b32 v255, 1, 43
	s_branch .LBB0_543

.LBB0_542:
	s_ashr_i32 s5, s4, 5
	s_mul_i32 s5, s5, 36
	s_and_b32 s4, s4, 31
	s_add_i32 s4, s4, s5
	s_add_i32 s5, s4, 4
	s_cmp_lg_u32 s64, 0
	s_cbranch_scc1 .LBB0_557
	v_readlane_b32 s4, v255, 43
	s_nop 1
	s_cmp_lg_u32 s4, 0
	s_cbranch_scc1 .LBB0_557
	s_nop 0
	v_writelane_b32 v255, 1, 43
